# pb2 + DFT stage-2 table: first four loads issued before the barrier that ends the LRU light pass, store-drain waits dropped
# baseline (speedup 1.0000x reference)
.LBB0_583:
	v_lshlrev_b32_e32 v246, 4, v0
	global_load_dwordx4 v[220:223], v246, s[70:71]
	s_add_u32 s100, s70, 0x2000
	s_addc_u32 s101, s71, 0
	global_load_dwordx4 v[224:227], v246, s[100:101]
	s_add_u32 s100, s70, 0x4000
	s_addc_u32 s101, s71, 0
	global_load_dwordx4 v[238:241], v246, s[100:101]
	s_add_u32 s100, s70, 0x6000
	s_addc_u32 s101, s71, 0
	global_load_dwordx4 v[242:245], v246, s[100:101]
	s_movk_i32 s0, 0x1000
	v_cmp_gt_i32_e32 vcc, s0, v0
	s_waitcnt lgkmcnt(0)
	s_barrier
	s_and_saveexec_b64 s[0:1], vcc
	s_xor_b64 s[0:1], exec, s[0:1]
	s_cbranch_execz .LBB0_587
	v_and_b32_e32 v3, 15, v0
	v_lshlrev_b32_e32 v2, 3, v3
	v_lshlrev_b32_e32 v4, 4, v3
	s_mov_b64 s[10:11], 0
	v_lshlrev_b32_e32 v2, 1, v2
	v_mov_b32_e32 v5, v0
.LBB0_585:
	v_lshlrev_b32_e32 v4, 4, v0
	v_add_u32_e32 v5, 0x2000, v4
	v_add_u32_e32 v6, 0x4000, v4
	v_add_u32_e32 v7, 0x6000, v4
	v_add_u32_e32 v8, 0x8000, v4
	v_add_u32_e32 v9, 0xa000, v4
	v_add_u32_e32 v10, 0xc000, v4
	v_add_u32_e32 v11, 0xe000, v4
	v_lshrrev_b32_e32 v2, 4, v0
	v_mul_u32_u24_e32 v2, 0x110, v2
	v_and_b32_e32 v3, 15, v0
	v_lshl_add_u32 v2, v3, 4, v2
	v_add_u32_e32 v3, v234, v2
	v_add_u32_e32 v2, v235, v2
	s_waitcnt vmcnt(3)
	ds_write_b128 v2, v[220:223]
	global_load_dwordx4 v[220:223], v8, s[70:71]
	s_waitcnt vmcnt(3)
	ds_write_b128 v2, v[224:227] offset:8704
	global_load_dwordx4 v[224:227], v9, s[70:71]
	s_waitcnt vmcnt(3)
	ds_write_b128 v2, v[238:241] offset:17408
	global_load_dwordx4 v[238:241], v10, s[70:71]
	s_waitcnt vmcnt(3)
	ds_write_b128 v2, v[242:245] offset:26112
	global_load_dwordx4 v[242:245], v11, s[70:71]
	s_waitcnt vmcnt(3)
	ds_write_b128 v3, v[220:223]
	s_waitcnt vmcnt(2)
	ds_write_b128 v3, v[224:227] offset:8704
	s_waitcnt vmcnt(1)
	ds_write_b128 v3, v[238:241] offset:17408
	s_waitcnt vmcnt(0)
	ds_write_b128 v3, v[242:245] offset:26112
	s_or_b64 exec, exec, s[10:11]
